# P1 bias vectors of the non-conv tiles also LDS-DMA-prefetched during the K-loop (on top of the P6 operand prefetch); those epilogues no longer drain vmcnt(0)
# baseline (speedup 1.0000x reference)
;     __device__ __forceinline__ void operator()(EPI_ARGS) const {
;     ...
;         bf16_t* base; int ldc, colt, mode;
;         if (pn < 4) { base = upool; ldc = PW; colt = pn * 256; mode = 0; }
;         else if (pn < 12) { base = ulru; ldc = LW; colt = (pn - 4) * 256; mode = 0; }
;         else if (pn < 20) { base = gelu_u; ldc = LW; colt = (pn - 12) * 256; mode = 1; }
;         else { base = gates; ldc = 2 * D; colt = (pn - 20) * 256; mode = 2; }
;         const int col0 = colt + wc * 32 + 8 * fq;
;         const float* bsrc = (mode == 2) ? b_gate : zeros;
;         f32x4 bv[2][2];
; #pragma unroll
;         for (int bj = 0; bj < 2; ++bj)
; #pragma unroll
;             for (int n = 0; n < 2; ++n) bv[bj][n] = *(const f32x4*)(bsrc + col0 + bj * 128 + 4 * n);
.LBB0_122:
	v_readfirstlane_b32 s76, v212
	s_lshr_b32 s76, s76, 6
	s_xor_b32 s76, s76, 4
	s_or_b32 s77, s76, s87
	s_cmp_lg_u32 s77, 0
	s_cbranch_scc1 .Lp1pf_skip
	s_add_i32 s76, s13, -4
	s_cmp_lt_u32 s76, 8
	s_cbranch_scc1 .Lp1pf_skip
	s_lshl_b32 s76, s13, 10
	s_mov_b32 s77, 0
	s_cmp_lt_u32 s13, 4
	s_cbranch_scc1 .Lp1pf_z
	s_movk_i32 s77, 0x3000
	s_cmp_lt_u32 s13, 20
	s_cbranch_scc1 .Lp1pf_z
	s_sub_u32 s76, s76, 0x5000
	v_mov_b32_e32 v220, s58
	v_mov_b32_e32 v221, s59
	s_branch .Lp1pf_go
.Lp1pf_z:
	s_sub_u32 s76, s76, s77
	v_mov_b32_e32 v220, s68
	v_mov_b32_e32 v221, s69
.Lp1pf_go:
	v_and_b32_e32 v222, 63, v212
	v_lshlrev_b32_e32 v222, 4, v222
	v_add_u32_e32 v222, s76, v222
	v_mov_b32_e32 v223, 0
	v_lshl_add_u64 v[220:221], v[220:221], 0, v[222:223]
	s_mov_b32 m0, 0x20400
	s_nop 0
	global_load_lds_dwordx4 v[220:221], off

;     __device__ __forceinline__ void operator()(EPI_ARGS) const {
;     ...
;         const int col0 = colt + wc * 32 + 8 * fq;
;         const float* bsrc = (mode == 2) ? b_gate : zeros;
;         f32x4 bv[2][2];
; #pragma unroll
;         for (int bj = 0; bj < 2; ++bj)
; #pragma unroll
;             for (int n = 0; n < 2; ++n) bv[bj][n] = *(const f32x4*)(bsrc + col0 + bj * 128 + 4 * n);
; #pragma unroll
;         for (int ai = 0; ai < 2; ++ai)
; #pragma unroll
;             for (int m = 0; m < 4; ++m) {
;                 const int row = ROW_OF(ai, m);
;                 bf16_t* rowp = base + (size_t)row * ldc + col0;
; #pragma unroll
;                 for (int bj = 0; bj < 2; ++bj) {
;                     f32x4 v0 = acc[ai][bj][m][0], v1 = acc[ai][bj][m][1];
;                     v0 = v0 + bv[bj][0]; v1 = v1 + bv[bj][1];
;                     if (mode == 1) { v0 = gelu4(v0); v1 = gelu4(v1); }
;                     else if (mode == 2) { v0 = sigmoid4(v0); v1 = sigmoid4(v1); }
.LBB0_178:
	s_xor_b64 s[6:7], s[0:1], -1
	s_add_i32 s0, s34, s27
	v_lshl_add_u32 v144, v176, 3, s0
	s_and_b64 s[0:1], s[4:5], exec
	s_cselect_b32 s0, s59, s69
	s_cselect_b32 s1, s58, s68
	v_mov_b32_e32 v128, s1
	v_mov_b32_e32 v129, s0
	v_ashrrev_i32_e32 v145, 31, v144
	v_lshl_add_u64 v[132:133], v[144:145], 2, v[128:129]
	v_lshl_add_u32 v229, v207, 3, s27
	v_lshlrev_b32_e32 v229, 2, v229
	v_add_u32_e32 v229, 0x20400, v229
	ds_read_b128 v[136:139], v229 offset:16
	ds_read_b128 v[140:143], v229
	ds_read_b128 v[128:131], v229 offset:528
	s_nop 0
	ds_read_b128 v[132:135], v229 offset:512
	v_cndmask_b32_e64 v154, 0, 1, s[4:5]
	s_mov_b64 s[96:97], -1
	s_and_b64 vcc, exec, s[6:7]
	v_cmp_ne_u32_e64 s[0:1], 1, v154
	s_waitcnt lgkmcnt(0)
	v_pk_add_f32 v[146:147], v[122:123], v[138:139]
	v_pk_add_f32 v[150:151], v[126:127], v[142:143]
	v_pk_add_f32 v[152:153], v[124:125], v[140:141]
	v_pk_add_f32 v[148:149], v[120:121], v[136:137]
	s_cbranch_vccz .LBB0_182
	s_and_b64 vcc, exec, s[0:1]
	v_mov_b32_e32 v161, v147
	v_mov_b32_e32 v160, v146
	v_mov_b32_e32 v159, v149
	v_mov_b32_e32 v158, v148
	v_mov_b32_e32 v157, v151
	v_mov_b32_e32 v156, v150
	v_mov_b32_e32 v155, v153
	v_mov_b32_e32 v154, v152
	s_cbranch_vccnz .LBB0_181
	v_mul_f32_e32 v154, 0xbfb8aa3b, v152
	v_mul_f32_e32 v155, 0xbfb8aa3b, v153
	v_mul_f32_e32 v156, 0xbfb8aa3b, v150
	v_mul_f32_e32 v157, 0xbfb8aa3b, v151
	v_mul_f32_e32 v158, 0xbfb8aa3b, v148
	v_mul_f32_e32 v159, 0xbfb8aa3b, v149
	v_mul_f32_e32 v160, 0xbfb8aa3b, v146
	v_mul_f32_e32 v161, 0xbfb8aa3b, v147
	v_exp_f32_e32 v154, v154
	v_exp_f32_e32 v155, v155
	v_exp_f32_e32 v156, v156
	v_exp_f32_e32 v157, v157
	v_exp_f32_e32 v158, v158
	v_exp_f32_e32 v159, v159
	v_exp_f32_e32 v160, v160
	v_exp_f32_e32 v161, v161
	v_add_f32_e32 v154, 1.0, v154
	v_add_f32_e32 v155, 1.0, v155
	v_add_f32_e32 v156, 1.0, v156
	v_add_f32_e32 v157, 1.0, v157
	v_add_f32_e32 v158, 1.0, v158
	v_add_f32_e32 v159, 1.0, v159
	v_add_f32_e32 v160, 1.0, v160
	v_add_f32_e32 v161, 1.0, v161
	v_rcp_f32_e32 v154, v154
	v_rcp_f32_e32 v155, v155
	v_rcp_f32_e32 v156, v156
	v_rcp_f32_e32 v157, v157
	v_rcp_f32_e32 v158, v158
	v_rcp_f32_e32 v159, v159
	v_rcp_f32_e32 v160, v160
	v_rcp_f32_e32 v161, v161
